# P0 rebalanced: the 768 waves that own a layer-0 adaLN item skip weight-conversion items; the other 1280 waves take all 5408 items
# speedup vs baseline: 1.0033x; 1.0033x over previous
; #define LAS __attribute__((address_space(3)))
; DI void wave_lds_fence() { __builtin_amdgcn_fence(__ATOMIC_RELEASE, "wavefront"); __builtin_amdgcn_wave_barrier(); __builtin_amdgcn_fence(__ATOMIC_ACQUIRE, "wavefront"); }
; template <int MODE> DI void transpose_item(const float* __restrict__ W, int K, int N, bf16_t* WT, LAS float* scr, int item, int lane) {
;     const int nblk = (N + 31) / 32, kb = item / nblk, nb = item % nblk, k0 = 64 * kb, n0 = 32 * nb;
;     const int ncol = n0 + (lane & 31); const bool okc = ncol < N;
;     float tv[32];
; #pragma unroll
;     for (int i = 0; i < 32; ++i) { const int kk = 2 * i + (lane >> 5); tv[i] = okc ? W[(size_t)(k0 + kk) * N + ncol] : 0.f; }
; #pragma unroll
;     for (int i = 0; i < 32; ++i) { const int kk = 2 * i + (lane >> 5); scr[kk * 33 + (lane & 31)] = tv[i]; }
;     wave_lds_fence();
;     const int c = lane & 7;
; DI void convert_items(const Params& P, LAS unsigned char* lds, int it0, int it1, int gw, int NGW, int wave, int lane) {
;     LAS float* scr = (LAS float*)(lds + wave * 16384);
;     bf16_t* WIN = (bf16_t*)(P.ws + WS_WIN); bf16_t* WOUT = (bf16_t*)(P.ws + WS_WOUT); bf16_t* WGU = (bf16_t*)(P.ws + WS_WGU); bf16_t* WDN = (bf16_t*)(P.ws + WS_WDN);
;     for (int it = it0 + gw; it < it1; it += NGW) {
;         const int l = it / I_L; int r = it % I_L;
;         if (r < I_IN) { transpose_item<1>(P.w_in + (size_t)l * D * INC, D, INC, WIN + (size_t)l * NPROJ * D, scr, r, lane); continue; } r -= I_IN;
.LBB0_730:
	s_cmpk_lt_i32 s18, 0x300
	s_waitcnt vmcnt(0)
	v_and_b32_e32 v12, 31, v241
	s_cbranch_scc1 .LBB0_829
	v_readlane_b32 s0, v254, 56
	v_readlane_b32 s1, v254, 57
	s_add_u32 s10, s0, 0x100000
	s_addc_u32 s11, s1, 0
	s_lshl_b32 s0, s6, 14
	v_lshlrev_b32_e32 v0, 3, v240
	s_add_i32 s0, s0, 0
	v_and_b32_e32 v13, 31, v241
	v_lshrrev_b32_e32 v14, 5, v240
	v_lshrrev_b32_e32 v15, 3, v240
	v_and_b32_e32 v0, 56, v0
	v_lshl_add_u32 v1, v13, 2, s0
	v_mul_u32_u24_e32 v2, 0x84, v14
	v_mul_u32_u24_e32 v3, 0x84, v0
	v_lshlrev_b32_e32 v4, 2, v15
	v_add3_u32 v16, s0, v3, v4
	v_or_b32_e32 v17, 8, v15
	v_or_b32_e32 v18, 16, v15
	v_or_b32_e32 v19, 24, v15
	v_add_u32_e32 v20, v1, v2
	v_lshlrev_b32_e32 v96, 1, v0
	s_add_i32 s6, s18, 0xfffffd00
	s_branch .LBB0_735

; DI void convert_items(const Params& P, LAS unsigned char* lds, int it0, int it1, int gw, int NGW, int wave, int lane) {
;     ...
;     for (int it = it0 + gw; it < it1; it += NGW) {
;         const int l = it / I_L; int r = it % I_L;
;         if (r < I_IN) { transpose_item<1>(P.w_in + (size_t)l * D * INC, D, INC, WIN + (size_t)l * NPROJ * D, scr, r, lane); continue; } r -= I_IN;
.LBB0_734:
	s_or_b64 exec, exec, s[0:1]
	s_addk_i32 s6, 0x500
	s_cmpk_lt_i32 s6, 0x1520
	s_cbranch_scc0 .LBB0_829
